# barriers: non-leader workgroups poll the TOP generation word directly (one hop less than the per-XCD generation word)
# baseline (speedup 1.0000x reference)
; __device__ __forceinline__ unsigned xb_ld(unsigned* p)              { return __hip_atomic_load(p, __ATOMIC_RELAXED, __HIP_MEMORY_SCOPE_AGENT); }
; __device__ __forceinline__ unsigned xb_add(unsigned* p, unsigned v) { return __hip_atomic_fetch_add(p, v, __ATOMIC_RELAXED, __HIP_MEMORY_SCOPE_AGENT); }
; #define XB_SPIN(cond, bar) do { unsigned _sp = 0; while (cond) { __builtin_amdgcn_s_sleep(1); \
;     if ((++_sp & 255u) == 0u) { if (xb_ld(&(bar)[XB_TMO])) break; if (_sp > XB_SPIN_CAP) { atomicAdd(&(bar)[XB_TMO], 1u); break; } } } } while (0)
; __device__ __forceinline__ void xcd_barrier(const XcdBarrier& b) {
;     ...
;         const unsigned old = xb_add(&bar[XB_XSUB(b.x)], 1u);
;         const unsigned gen = old / nloc;
;         if (old + 1u == (gen + 1u) * nloc) {
;             __builtin_amdgcn_fence(__ATOMIC_RELEASE, "agent");
;             asm volatile("s_waitcnt vmcnt(0)" ::: "memory");
;             const unsigned og = xb_add(&bar[XB_TOP], 1u);
;             const unsigned tg = og / nx;
;             if (og + 1u == (tg + 1u) * nx) xb_add(&bar[XB_TOPGEN], 1u);
;             else XB_SPIN(xb_ld(&bar[XB_TOPGEN]) == tg, bar);
;             __builtin_amdgcn_fence(__ATOMIC_ACQUIRE, "agent");
;             xb_add(&bar[XB_XGEN(b.x)], 1u);
;             asm volatile("s_waitcnt vmcnt(0)" ::: "memory");
;         } else {
;             XB_SPIN(xb_ld(&bar[XB_XGEN(b.x)]) == gen, bar);
.LBB0_120:
	s_or_b64 exec, exec, s[38:39]
	v_cvt_f32_u32_e32 v4, v2
	s_waitcnt vmcnt(0)
	v_readfirstlane_b32 s8, v3
	v_sub_u32_e32 v3, 0, v2
	v_rcp_iflag_f32_e32 v4, v4
	v_add_u32_e32 v5, s8, v1
	v_mul_f32_e32 v4, 0x4f7ffffe, v4
	v_cvt_u32_f32_e32 v4, v4
	v_mul_lo_u32 v1, v3, v4
	v_mul_hi_u32 v1, v4, v1
	v_add_u32_e32 v1, v4, v1
	v_mul_hi_u32 v1, v5, v1
	v_mul_lo_u32 v3, v1, v2
	v_sub_u32_e32 v3, v5, v3
	v_add_u32_e32 v4, 1, v1
	v_cmp_ge_u32_e32 vcc, v3, v2
	s_nop 1
	v_cndmask_b32_e32 v1, v1, v4, vcc
	v_sub_u32_e32 v4, v3, v2
	v_cndmask_b32_e32 v3, v3, v4, vcc
	v_add_u32_e32 v4, 1, v1
	v_cmp_ge_u32_e32 vcc, v3, v2
	v_add_u32_e32 v3, 1, v5
	s_nop 0
	v_cndmask_b32_e32 v1, v1, v4, vcc
	v_mul_lo_u32 v4, v2, v1
	v_add_u32_e32 v2, v4, v2
	v_cmp_ne_u32_e32 vcc, v3, v2
	s_and_saveexec_b64 s[8:9], vcc
	s_xor_b64 s[8:9], exec, s[8:9]
	s_cbranch_execz .LBB0_134
	s_waitcnt lgkmcnt(0)
	s_add_u32 s42, s34, 0x83500
	s_addc_u32 s43, s35, 0
	v_mov_b32_e32 v0, 0
	global_load_dword v0, v0, s[42:43] sc1
	s_waitcnt vmcnt(0)
	v_cmp_eq_u32_e32 vcc, v0, v1
	s_and_saveexec_b64 s[38:39], vcc
	s_cbranch_execz .LBB0_133
	s_add_u32 s40, s34, 0x80200
	s_addc_u32 s41, s35, 0
	s_mov_b32 s10, 1
	s_mov_b64 s[44:45], 0
	v_mov_b32_e32 v0, 0
	s_branch .LBB0_124

; __device__ __forceinline__ unsigned xb_ld(unsigned* p)              { return __hip_atomic_load(p, __ATOMIC_RELAXED, __HIP_MEMORY_SCOPE_AGENT); }
; __device__ __forceinline__ unsigned xb_add(unsigned* p, unsigned v) { return __hip_atomic_fetch_add(p, v, __ATOMIC_RELAXED, __HIP_MEMORY_SCOPE_AGENT); }
; #define XB_SPIN(cond, bar) do { unsigned _sp = 0; while (cond) { __builtin_amdgcn_s_sleep(1); \
;     if ((++_sp & 255u) == 0u) { if (xb_ld(&(bar)[XB_TMO])) break; if (_sp > XB_SPIN_CAP) { atomicAdd(&(bar)[XB_TMO], 1u); break; } } } } while (0)
; __device__ __forceinline__ void xcd_barrier(const XcdBarrier& b) {
;     ...
;         const unsigned gen = old / nloc;
;         if (old + 1u == (gen + 1u) * nloc) {
;             __builtin_amdgcn_fence(__ATOMIC_RELEASE, "agent");
;             asm volatile("s_waitcnt vmcnt(0)" ::: "memory");
;             const unsigned og = xb_add(&bar[XB_TOP], 1u);
;             const unsigned tg = og / nx;
;             if (og + 1u == (tg + 1u) * nx) xb_add(&bar[XB_TOPGEN], 1u);
;             else XB_SPIN(xb_ld(&bar[XB_TOPGEN]) == tg, bar);
;             __builtin_amdgcn_fence(__ATOMIC_ACQUIRE, "agent");
;             xb_add(&bar[XB_XGEN(b.x)], 1u);
;             asm volatile("s_waitcnt vmcnt(0)" ::: "memory");
;         } else {
;             XB_SPIN(xb_ld(&bar[XB_XGEN(b.x)]) == gen, bar);
.LBB0_367:
	s_or_b64 exec, exec, s[12:13]
	v_cvt_f32_u32_e32 v4, v2
	s_waitcnt vmcnt(0)
	v_readfirstlane_b32 s8, v3
	v_sub_u32_e32 v3, 0, v2
	v_rcp_iflag_f32_e32 v4, v4
	v_add_u32_e32 v5, s8, v1
	v_mul_f32_e32 v4, 0x4f7ffffe, v4
	v_cvt_u32_f32_e32 v4, v4
	v_mul_lo_u32 v1, v3, v4
	v_mul_hi_u32 v1, v4, v1
	v_add_u32_e32 v1, v4, v1
	v_mul_hi_u32 v1, v5, v1
	v_mul_lo_u32 v3, v1, v2
	v_sub_u32_e32 v3, v5, v3
	v_add_u32_e32 v4, 1, v1
	v_cmp_ge_u32_e32 vcc, v3, v2
	s_nop 1
	v_cndmask_b32_e32 v1, v1, v4, vcc
	v_sub_u32_e32 v4, v3, v2
	v_cndmask_b32_e32 v3, v3, v4, vcc
	v_add_u32_e32 v4, 1, v1
	v_cmp_ge_u32_e32 vcc, v3, v2
	v_add_u32_e32 v3, 1, v5
	s_nop 0
	v_cndmask_b32_e32 v1, v1, v4, vcc
	v_mul_lo_u32 v4, v2, v1
	v_add_u32_e32 v2, v4, v2
	v_cmp_ne_u32_e32 vcc, v3, v2
	s_and_saveexec_b64 s[8:9], vcc
	s_xor_b64 s[8:9], exec, s[8:9]
	s_cbranch_execz .LBB0_381
	s_waitcnt lgkmcnt(0)
	s_add_u32 s16, s34, 0x83500
	s_addc_u32 s17, s35, 0
	v_mov_b32_e32 v0, 0
	global_load_dword v0, v0, s[16:17] sc1
	s_waitcnt vmcnt(0)
	v_cmp_eq_u32_e32 vcc, v0, v1
	s_and_saveexec_b64 s[12:13], vcc
	s_cbranch_execz .LBB0_380
	s_add_u32 s14, s34, 0x80200
	s_addc_u32 s15, s35, 0
	s_mov_b32 s10, 1
	s_mov_b64 s[20:21], 0
	v_mov_b32_e32 v0, 0
	s_branch .LBB0_371

; __device__ __forceinline__ unsigned xb_ld(unsigned* p)              { return __hip_atomic_load(p, __ATOMIC_RELAXED, __HIP_MEMORY_SCOPE_AGENT); }
; __device__ __forceinline__ unsigned xb_add(unsigned* p, unsigned v) { return __hip_atomic_fetch_add(p, v, __ATOMIC_RELAXED, __HIP_MEMORY_SCOPE_AGENT); }
; #define XB_SPIN(cond, bar) do { unsigned _sp = 0; while (cond) { __builtin_amdgcn_s_sleep(1); \
;     if ((++_sp & 255u) == 0u) { if (xb_ld(&(bar)[XB_TMO])) break; if (_sp > XB_SPIN_CAP) { atomicAdd(&(bar)[XB_TMO], 1u); break; } } } } while (0)
; __device__ __forceinline__ void xcd_barrier(const XcdBarrier& b) {
;     ...
;         const unsigned old = xb_add(&bar[XB_XSUB(b.x)], 1u);
;         const unsigned gen = old / nloc;
;         if (old + 1u == (gen + 1u) * nloc) {
;             __builtin_amdgcn_fence(__ATOMIC_RELEASE, "agent");
;             asm volatile("s_waitcnt vmcnt(0)" ::: "memory");
;             const unsigned og = xb_add(&bar[XB_TOP], 1u);
;             const unsigned tg = og / nx;
;             if (og + 1u == (tg + 1u) * nx) xb_add(&bar[XB_TOPGEN], 1u);
;             else XB_SPIN(xb_ld(&bar[XB_TOPGEN]) == tg, bar);
;             __builtin_amdgcn_fence(__ATOMIC_ACQUIRE, "agent");
;             xb_add(&bar[XB_XGEN(b.x)], 1u);
;             asm volatile("s_waitcnt vmcnt(0)" ::: "memory");
;         } else {
;             XB_SPIN(xb_ld(&bar[XB_XGEN(b.x)]) == gen, bar);
.LBB0_484:
	v_readlane_b32 s6, v240, 2
	s_lshl_b32 s6, s6, 8
	s_add_u32 s6, s60, s6
	s_addc_u32 s7, s61, 0
	v_mov_b32_e32 v1, 0x1000
	v_mov_b32_e32 v3, 1
	global_atomic_add v3, v1, v3, s[6:7] offset:1024 sc0
	v_cvt_f32_u32_e32 v1, v2
	v_sub_u32_e32 v4, 0, v2
	v_rcp_iflag_f32_e32 v1, v1
	s_nop 0
	v_mul_f32_e32 v1, 0x4f7ffffe, v1
	v_cvt_u32_f32_e32 v1, v1
	v_mul_lo_u32 v4, v4, v1
	v_mul_hi_u32 v4, v1, v4
	v_add_u32_e32 v1, v1, v4
	s_waitcnt vmcnt(0)
	v_mul_hi_u32 v1, v3, v1
	v_mul_lo_u32 v4, v1, v2
	v_sub_u32_e32 v4, v3, v4
	v_add_u32_e32 v5, 1, v1
	v_cmp_ge_u32_e32 vcc, v4, v2
	v_add_u32_e32 v3, 1, v3
	s_nop 0
	v_cndmask_b32_e32 v1, v1, v5, vcc
	v_sub_u32_e32 v5, v4, v2
	v_cndmask_b32_e32 v4, v4, v5, vcc
	v_add_u32_e32 v5, 1, v1
	v_cmp_ge_u32_e32 vcc, v4, v2
	s_nop 1
	v_cndmask_b32_e32 v1, v1, v5, vcc
	v_mul_lo_u32 v4, v2, v1
	v_add_u32_e32 v2, v4, v2
	v_cmp_ne_u32_e32 vcc, v3, v2
	s_and_saveexec_b64 s[8:9], vcc
	s_xor_b64 s[8:9], exec, s[8:9]
	s_cbranch_execz .LBB0_498
	s_waitcnt lgkmcnt(0)
	s_add_u32 s14, s60, 0x3500
	s_addc_u32 s15, s61, 0
	v_mov_b32_e32 v0, 0
	global_load_dword v0, v0, s[14:15] sc1
	s_waitcnt vmcnt(0)
	v_cmp_eq_u32_e32 vcc, v0, v1
	s_and_saveexec_b64 s[12:13], vcc
	s_cbranch_execz .LBB0_497
	s_mov_b32 s10, 1
	s_mov_b64 s[16:17], 0
	v_mov_b32_e32 v0, 0
	s_branch .LBB0_488

; __device__ __forceinline__ unsigned xb_ld(unsigned* p)              { return __hip_atomic_load(p, __ATOMIC_RELAXED, __HIP_MEMORY_SCOPE_AGENT); }
; __device__ __forceinline__ unsigned xb_add(unsigned* p, unsigned v) { return __hip_atomic_fetch_add(p, v, __ATOMIC_RELAXED, __HIP_MEMORY_SCOPE_AGENT); }
; #define XB_SPIN(cond, bar) do { unsigned _sp = 0; while (cond) { __builtin_amdgcn_s_sleep(1); \
;     if ((++_sp & 255u) == 0u) { if (xb_ld(&(bar)[XB_TMO])) break; if (_sp > XB_SPIN_CAP) { atomicAdd(&(bar)[XB_TMO], 1u); break; } } } } while (0)
; __device__ __forceinline__ void xcd_barrier(const XcdBarrier& b) {
;     ...
;         const unsigned gen = old / nloc;
;         if (old + 1u == (gen + 1u) * nloc) {
;             __builtin_amdgcn_fence(__ATOMIC_RELEASE, "agent");
;             asm volatile("s_waitcnt vmcnt(0)" ::: "memory");
;             const unsigned og = xb_add(&bar[XB_TOP], 1u);
;             const unsigned tg = og / nx;
;             if (og + 1u == (tg + 1u) * nx) xb_add(&bar[XB_TOPGEN], 1u);
;             else XB_SPIN(xb_ld(&bar[XB_TOPGEN]) == tg, bar);
;             __builtin_amdgcn_fence(__ATOMIC_ACQUIRE, "agent");
;             xb_add(&bar[XB_XGEN(b.x)], 1u);
;             asm volatile("s_waitcnt vmcnt(0)" ::: "memory");
;         } else {
;             XB_SPIN(xb_ld(&bar[XB_XGEN(b.x)]) == gen, bar);
.LBB0_636:
	s_or_b64 exec, exec, s[16:17]
	v_cvt_f32_u32_e32 v4, v2
	s_waitcnt vmcnt(0)
	v_readfirstlane_b32 s10, v3
	v_sub_u32_e32 v3, 0, v2
	v_rcp_iflag_f32_e32 v4, v4
	v_add_u32_e32 v5, s10, v1
	v_mul_f32_e32 v4, 0x4f7ffffe, v4
	v_cvt_u32_f32_e32 v4, v4
	v_mul_lo_u32 v1, v3, v4
	v_mul_hi_u32 v1, v4, v1
	v_add_u32_e32 v1, v4, v1
	v_mul_hi_u32 v1, v5, v1
	v_mul_lo_u32 v3, v1, v2
	v_sub_u32_e32 v3, v5, v3
	v_add_u32_e32 v4, 1, v1
	v_cmp_ge_u32_e32 vcc, v3, v2
	s_nop 1
	v_cndmask_b32_e32 v1, v1, v4, vcc
	v_sub_u32_e32 v4, v3, v2
	v_cndmask_b32_e32 v3, v3, v4, vcc
	v_add_u32_e32 v4, 1, v1
	v_cmp_ge_u32_e32 vcc, v3, v2
	v_add_u32_e32 v3, 1, v5
	s_nop 0
	v_cndmask_b32_e32 v1, v1, v4, vcc
	v_mul_lo_u32 v4, v2, v1
	v_add_u32_e32 v2, v4, v2
	v_cmp_ne_u32_e32 vcc, v3, v2
	s_and_saveexec_b64 s[10:11], vcc
	s_xor_b64 s[12:13], exec, s[10:11]
	s_cbranch_execz .LBB0_650
	s_waitcnt lgkmcnt(0)
	s_add_u32 s26, s34, 0x83500
	s_addc_u32 s27, s35, 0
	v_mov_b32_e32 v0, 0
	global_load_dword v0, v0, s[26:27] sc1
	s_waitcnt vmcnt(0)
	v_cmp_eq_u32_e32 vcc, v0, v1
	s_and_saveexec_b64 s[16:17], vcc
	s_cbranch_execz .LBB0_649
	s_add_u32 s20, s34, 0x80200
	s_addc_u32 s21, s35, 0
	s_mov_b32 s10, 1
	s_mov_b64 s[36:37], 0
	v_mov_b32_e32 v0, 0
	s_branch .LBB0_640

; __device__ __forceinline__ unsigned xb_ld(unsigned* p)              { return __hip_atomic_load(p, __ATOMIC_RELAXED, __HIP_MEMORY_SCOPE_AGENT); }
; __device__ __forceinline__ unsigned xb_add(unsigned* p, unsigned v) { return __hip_atomic_fetch_add(p, v, __ATOMIC_RELAXED, __HIP_MEMORY_SCOPE_AGENT); }
; #define XB_SPIN(cond, bar) do { unsigned _sp = 0; while (cond) { __builtin_amdgcn_s_sleep(1); \
;     if ((++_sp & 255u) == 0u) { if (xb_ld(&(bar)[XB_TMO])) break; if (_sp > XB_SPIN_CAP) { atomicAdd(&(bar)[XB_TMO], 1u); break; } } } } while (0)
; __device__ __forceinline__ void xcd_barrier(const XcdBarrier& b) {
;     ...
;         const unsigned gen = old / nloc;
;         if (old + 1u == (gen + 1u) * nloc) {
;             __builtin_amdgcn_fence(__ATOMIC_RELEASE, "agent");
;             asm volatile("s_waitcnt vmcnt(0)" ::: "memory");
;             const unsigned og = xb_add(&bar[XB_TOP], 1u);
;             const unsigned tg = og / nx;
;             if (og + 1u == (tg + 1u) * nx) xb_add(&bar[XB_TOPGEN], 1u);
;             else XB_SPIN(xb_ld(&bar[XB_TOPGEN]) == tg, bar);
;             __builtin_amdgcn_fence(__ATOMIC_ACQUIRE, "agent");
;             xb_add(&bar[XB_XGEN(b.x)], 1u);
;             asm volatile("s_waitcnt vmcnt(0)" ::: "memory");
;         } else {
;             XB_SPIN(xb_ld(&bar[XB_XGEN(b.x)]) == gen, bar);
.LBB0_716:
	s_or_b64 exec, exec, s[16:17]
	v_cvt_f32_u32_e32 v4, v2
	s_waitcnt vmcnt(0)
	v_readfirstlane_b32 s10, v3
	v_sub_u32_e32 v3, 0, v2
	v_rcp_iflag_f32_e32 v4, v4
	v_add_u32_e32 v5, s10, v1
	v_mul_f32_e32 v4, 0x4f7ffffe, v4
	v_cvt_u32_f32_e32 v4, v4
	v_mul_lo_u32 v1, v3, v4
	v_mul_hi_u32 v1, v4, v1
	v_add_u32_e32 v1, v4, v1
	v_mul_hi_u32 v1, v5, v1
	v_mul_lo_u32 v3, v1, v2
	v_sub_u32_e32 v3, v5, v3
	v_add_u32_e32 v4, 1, v1
	v_cmp_ge_u32_e32 vcc, v3, v2
	s_nop 1
	v_cndmask_b32_e32 v1, v1, v4, vcc
	v_sub_u32_e32 v4, v3, v2
	v_cndmask_b32_e32 v3, v3, v4, vcc
	v_add_u32_e32 v4, 1, v1
	v_cmp_ge_u32_e32 vcc, v3, v2
	v_add_u32_e32 v3, 1, v5
	s_nop 0
	v_cndmask_b32_e32 v1, v1, v4, vcc
	v_mul_lo_u32 v4, v2, v1
	v_add_u32_e32 v2, v4, v2
	v_cmp_ne_u32_e32 vcc, v3, v2
	s_and_saveexec_b64 s[10:11], vcc
	s_xor_b64 s[12:13], exec, s[10:11]
	s_cbranch_execz .LBB0_745
	s_waitcnt lgkmcnt(0)
	s_add_u32 s20, s34, 0x83500
	s_addc_u32 s21, s35, 0
	v_mov_b32_e32 v0, 0
	global_load_dword v0, v0, s[20:21] sc1
	s_waitcnt vmcnt(0)
	v_cmp_eq_u32_e32 vcc, v0, v1
	s_and_saveexec_b64 s[16:17], vcc
	s_cbranch_execz .LBB0_744
	s_add_u32 s18, s34, 0x80200
	s_addc_u32 s19, s35, 0
	s_mov_b32 s10, 1
	s_mov_b64 s[26:27], 0
	v_mov_b32_e32 v0, 0
	s_branch .LBB0_720

; __device__ __forceinline__ unsigned xb_ld(unsigned* p)              { return __hip_atomic_load(p, __ATOMIC_RELAXED, __HIP_MEMORY_SCOPE_AGENT); }
; __device__ __forceinline__ unsigned xb_add(unsigned* p, unsigned v) { return __hip_atomic_fetch_add(p, v, __ATOMIC_RELAXED, __HIP_MEMORY_SCOPE_AGENT); }
; #define XB_SPIN(cond, bar) do { unsigned _sp = 0; while (cond) { __builtin_amdgcn_s_sleep(1); \
;     if ((++_sp & 255u) == 0u) { if (xb_ld(&(bar)[XB_TMO])) break; if (_sp > XB_SPIN_CAP) { atomicAdd(&(bar)[XB_TMO], 1u); break; } } } } while (0)
; __device__ __forceinline__ void xcd_barrier(const XcdBarrier& b) {
;     ...
;         const unsigned old = xb_add(&bar[XB_XSUB(b.x)], 1u);
;         const unsigned gen = old / nloc;
;         if (old + 1u == (gen + 1u) * nloc) {
;             __builtin_amdgcn_fence(__ATOMIC_RELEASE, "agent");
;             asm volatile("s_waitcnt vmcnt(0)" ::: "memory");
;             const unsigned og = xb_add(&bar[XB_TOP], 1u);
;             const unsigned tg = og / nx;
;             if (og + 1u == (tg + 1u) * nx) xb_add(&bar[XB_TOPGEN], 1u);
;             else XB_SPIN(xb_ld(&bar[XB_TOPGEN]) == tg, bar);
;             __builtin_amdgcn_fence(__ATOMIC_ACQUIRE, "agent");
;             xb_add(&bar[XB_XGEN(b.x)], 1u);
;             asm volatile("s_waitcnt vmcnt(0)" ::: "memory");
;         } else {
;             XB_SPIN(xb_ld(&bar[XB_XGEN(b.x)]) == gen, bar);
.LBB0_731:
	v_readlane_b32 s4, v240, 2
	s_lshl_b32 s4, s4, 8
	s_add_u32 s4, s60, s4
	s_addc_u32 s5, s61, 0
	v_mov_b32_e32 v1, 0x1000
	v_mov_b32_e32 v3, 1
	global_atomic_add v3, v1, v3, s[4:5] offset:1024 sc0
	v_cvt_f32_u32_e32 v1, v2
	v_sub_u32_e32 v4, 0, v2
	v_rcp_iflag_f32_e32 v1, v1
	s_nop 0
	v_mul_f32_e32 v1, 0x4f7ffffe, v1
	v_cvt_u32_f32_e32 v1, v1
	v_mul_lo_u32 v4, v4, v1
	v_mul_hi_u32 v4, v1, v4
	v_add_u32_e32 v1, v1, v4
	s_waitcnt vmcnt(0)
	v_mul_hi_u32 v1, v3, v1
	v_mul_lo_u32 v4, v1, v2
	v_sub_u32_e32 v4, v3, v4
	v_add_u32_e32 v5, 1, v1
	v_cmp_ge_u32_e32 vcc, v4, v2
	v_add_u32_e32 v3, 1, v3
	s_nop 0
	v_cndmask_b32_e32 v1, v1, v5, vcc
	v_sub_u32_e32 v5, v4, v2
	v_cndmask_b32_e32 v4, v4, v5, vcc
	v_add_u32_e32 v5, 1, v1
	v_cmp_ge_u32_e32 vcc, v4, v2
	s_nop 1
	v_cndmask_b32_e32 v1, v1, v5, vcc
	v_mul_lo_u32 v4, v2, v1
	v_add_u32_e32 v2, v4, v2
	v_cmp_ne_u32_e32 vcc, v3, v2
	s_and_saveexec_b64 s[6:7], vcc
	s_xor_b64 s[6:7], exec, s[6:7]
	s_cbranch_execz .LBB0_762
	s_waitcnt lgkmcnt(0)
	s_add_u32 s12, s60, 0x3500
	s_addc_u32 s13, s61, 0
	v_mov_b32_e32 v0, 0
	global_load_dword v0, v0, s[12:13] sc1
	s_waitcnt vmcnt(0)
	v_cmp_eq_u32_e32 vcc, v0, v1
	s_and_saveexec_b64 s[8:9], vcc
	s_cbranch_execz .LBB0_761
	s_mov_b32 s10, 1
	s_mov_b64 s[16:17], 0
	v_mov_b32_e32 v0, 0
	s_branch .LBB0_735

; __device__ __forceinline__ unsigned xb_ld(unsigned* p)              { return __hip_atomic_load(p, __ATOMIC_RELAXED, __HIP_MEMORY_SCOPE_AGENT); }
; __device__ __forceinline__ unsigned xb_add(unsigned* p, unsigned v) { return __hip_atomic_fetch_add(p, v, __ATOMIC_RELAXED, __HIP_MEMORY_SCOPE_AGENT); }
; #define XB_SPIN(cond, bar) do { unsigned _sp = 0; while (cond) { __builtin_amdgcn_s_sleep(1); \
;     if ((++_sp & 255u) == 0u) { if (xb_ld(&(bar)[XB_TMO])) break; if (_sp > XB_SPIN_CAP) { atomicAdd(&(bar)[XB_TMO], 1u); break; } } } } while (0)
; __device__ __forceinline__ void xcd_barrier(const XcdBarrier& b) {
;     ...
;         const unsigned gen = old / nloc;
;         if (old + 1u == (gen + 1u) * nloc) {
;             __builtin_amdgcn_fence(__ATOMIC_RELEASE, "agent");
;             asm volatile("s_waitcnt vmcnt(0)" ::: "memory");
;             const unsigned og = xb_add(&bar[XB_TOP], 1u);
;             const unsigned tg = og / nx;
;             if (og + 1u == (tg + 1u) * nx) xb_add(&bar[XB_TOPGEN], 1u);
;             else XB_SPIN(xb_ld(&bar[XB_TOPGEN]) == tg, bar);
;             __builtin_amdgcn_fence(__ATOMIC_ACQUIRE, "agent");
;             xb_add(&bar[XB_XGEN(b.x)], 1u);
;             asm volatile("s_waitcnt vmcnt(0)" ::: "memory");
;         } else {
;             XB_SPIN(xb_ld(&bar[XB_XGEN(b.x)]) == gen, bar);
.LBB0_834:
	s_or_b64 exec, exec, s[12:13]
	v_cvt_f32_u32_e32 v4, v2
	s_waitcnt vmcnt(0)
	v_readfirstlane_b32 s8, v3
	v_sub_u32_e32 v3, 0, v2
	v_rcp_iflag_f32_e32 v4, v4
	v_add_u32_e32 v5, s8, v1
	v_mul_f32_e32 v4, 0x4f7ffffe, v4
	v_cvt_u32_f32_e32 v4, v4
	v_mul_lo_u32 v1, v3, v4
	v_mul_hi_u32 v1, v4, v1
	v_add_u32_e32 v1, v4, v1
	v_mul_hi_u32 v1, v5, v1
	v_mul_lo_u32 v3, v1, v2
	v_sub_u32_e32 v3, v5, v3
	v_add_u32_e32 v4, 1, v1
	v_cmp_ge_u32_e32 vcc, v3, v2
	s_nop 1
	v_cndmask_b32_e32 v1, v1, v4, vcc
	v_sub_u32_e32 v4, v3, v2
	v_cndmask_b32_e32 v3, v3, v4, vcc
	v_add_u32_e32 v4, 1, v1
	v_cmp_ge_u32_e32 vcc, v3, v2
	v_add_u32_e32 v3, 1, v5
	s_nop 0
	v_cndmask_b32_e32 v1, v1, v4, vcc
	v_mul_lo_u32 v4, v2, v1
	v_add_u32_e32 v2, v4, v2
	v_cmp_ne_u32_e32 vcc, v3, v2
	s_and_saveexec_b64 s[8:9], vcc
	s_xor_b64 s[8:9], exec, s[8:9]
	s_cbranch_execz .LBB0_848
	s_waitcnt lgkmcnt(0)
	s_add_u32 s18, s34, 0x83500
	s_addc_u32 s19, s35, 0
	v_mov_b32_e32 v0, 0
	global_load_dword v0, v0, s[18:19] sc1
	s_waitcnt vmcnt(0)
	v_cmp_eq_u32_e32 vcc, v0, v1
	s_and_saveexec_b64 s[12:13], vcc
	s_cbranch_execz .LBB0_847
	s_add_u32 s16, s34, 0x80200
	s_addc_u32 s17, s35, 0
	s_mov_b32 s10, 1
	s_mov_b64 s[20:21], 0
	v_mov_b32_e32 v0, 0
	s_branch .LBB0_838

; __device__ __forceinline__ unsigned xb_ld(unsigned* p)              { return __hip_atomic_load(p, __ATOMIC_RELAXED, __HIP_MEMORY_SCOPE_AGENT); }
; __device__ __forceinline__ unsigned xb_add(unsigned* p, unsigned v) { return __hip_atomic_fetch_add(p, v, __ATOMIC_RELAXED, __HIP_MEMORY_SCOPE_AGENT); }
; #define XB_SPIN(cond, bar) do { unsigned _sp = 0; while (cond) { __builtin_amdgcn_s_sleep(1); \
;     if ((++_sp & 255u) == 0u) { if (xb_ld(&(bar)[XB_TMO])) break; if (_sp > XB_SPIN_CAP) { atomicAdd(&(bar)[XB_TMO], 1u); break; } } } } while (0)
; __device__ __forceinline__ void xcd_barrier(const XcdBarrier& b) {
;     ...
;         const unsigned old = xb_add(&bar[XB_XSUB(b.x)], 1u);
;         const unsigned gen = old / nloc;
;         if (old + 1u == (gen + 1u) * nloc) {
;             __builtin_amdgcn_fence(__ATOMIC_RELEASE, "agent");
;             asm volatile("s_waitcnt vmcnt(0)" ::: "memory");
;             const unsigned og = xb_add(&bar[XB_TOP], 1u);
;             const unsigned tg = og / nx;
;             if (og + 1u == (tg + 1u) * nx) xb_add(&bar[XB_TOPGEN], 1u);
;             else XB_SPIN(xb_ld(&bar[XB_TOPGEN]) == tg, bar);
;             __builtin_amdgcn_fence(__ATOMIC_ACQUIRE, "agent");
;             xb_add(&bar[XB_XGEN(b.x)], 1u);
;             asm volatile("s_waitcnt vmcnt(0)" ::: "memory");
;         } else {
;             XB_SPIN(xb_ld(&bar[XB_XGEN(b.x)]) == gen, bar);
.LBB0_886:
	v_readlane_b32 s6, v240, 2
	s_lshl_b32 s6, s6, 8
	s_add_u32 s6, s60, s6
	s_addc_u32 s7, s61, 0
	v_mov_b32_e32 v1, 0x1000
	v_mov_b32_e32 v3, 1
	global_atomic_add v3, v1, v3, s[6:7] offset:1024 sc0
	v_cvt_f32_u32_e32 v1, v2
	v_sub_u32_e32 v4, 0, v2
	v_rcp_iflag_f32_e32 v1, v1
	s_nop 0
	v_mul_f32_e32 v1, 0x4f7ffffe, v1
	v_cvt_u32_f32_e32 v1, v1
	v_mul_lo_u32 v4, v4, v1
	v_mul_hi_u32 v4, v1, v4
	v_add_u32_e32 v1, v1, v4
	s_waitcnt vmcnt(0)
	v_mul_hi_u32 v1, v3, v1
	v_mul_lo_u32 v4, v1, v2
	v_sub_u32_e32 v4, v3, v4
	v_add_u32_e32 v5, 1, v1
	v_cmp_ge_u32_e32 vcc, v4, v2
	v_add_u32_e32 v3, 1, v3
	s_nop 0
	v_cndmask_b32_e32 v1, v1, v5, vcc
	v_sub_u32_e32 v5, v4, v2
	v_cndmask_b32_e32 v4, v4, v5, vcc
	v_add_u32_e32 v5, 1, v1
	v_cmp_ge_u32_e32 vcc, v4, v2
	s_nop 1
	v_cndmask_b32_e32 v1, v1, v5, vcc
	v_mul_lo_u32 v4, v2, v1
	v_add_u32_e32 v2, v4, v2
	v_cmp_ne_u32_e32 vcc, v3, v2
	s_and_saveexec_b64 s[8:9], vcc
	s_xor_b64 s[8:9], exec, s[8:9]
	s_cbranch_execz .LBB0_900
	s_waitcnt lgkmcnt(0)
	s_add_u32 s16, s60, 0x3500
	s_addc_u32 s17, s61, 0
	v_mov_b32_e32 v0, 0
	global_load_dword v0, v0, s[16:17] sc1
	s_waitcnt vmcnt(0)
	v_cmp_eq_u32_e32 vcc, v0, v1
	s_and_saveexec_b64 s[12:13], vcc
	s_cbranch_execz .LBB0_899
	s_mov_b32 s10, 1
	s_mov_b64 s[18:19], 0
	v_mov_b32_e32 v0, 0
	s_branch .LBB0_890
